# scan chain: counted wait vmcnt(24)->vmcnt(36) in the GDN state-scan loop (waits only for the DMA stage consumed, not the previous step's stores)
# speedup vs baseline: 1.0356x; 1.0356x over previous
; DI void phase_scan(KArgs args, LAS unsigned char* L, const Ctx& c) {
;     ...
;         SCAN_DMA(); SCAN_DMA(); SCAN_DMA(); SCAN_DMA(); SCAN_DMA();
;         asm volatile("s_waitcnt vmcnt(48)" ::: "memory"); SCAN_LOAD(0);
;         asm volatile("s_waitcnt vmcnt(36)" ::: "memory"); SCAN_LOAD(1);
;         for (int step = 0; step < nch; step += 2) {
;             SCAN_STEP(0, step);     asm volatile("s_waitcnt vmcnt(24)" ::: "memory"); SCAN_LOAD(0); SCAN_DMA();
;             SCAN_STEP(1, step + 1); asm volatile("s_waitcnt vmcnt(24)" ::: "memory"); SCAN_LOAD(1); SCAN_DMA();
.LBB0_649:
	s_add_i32 s14, s10, -6
	s_add_i32 s13, s10, -1
	s_lshr_b32 s6, s14, 6
	s_cmp_lt_u32 s14, 64
	s_cselect_b64 vcc, -1, 0
	s_cmp_eq_u32 s6, 1
	s_cselect_b64 s[4:5], -1, 0
	s_cmp_eq_u32 s6, 2
	s_cselect_b64 s[6:7], -1, 0
	v_cndmask_b32_e64 v172, v170, v169, s[6:7]
	v_cndmask_b32_e64 v172, v172, v168, s[4:5]
	v_cndmask_b32_e32 v172, v172, v1, vcc
	s_waitcnt lgkmcnt(0)
	v_lshlrev_b32_e32 v174, 16, v96
	v_readlane_b32 s4, v172, s14
	v_and_b32_e32 v175, 0xffff0000, v96
	v_lshlrev_b32_e32 v96, 16, v97
	v_and_b32_e32 v97, 0xffff0000, v97
	v_cvt_pk_bf16_f32 v133, v6, v7
	v_pk_fma_f32 v[6:7], v[6:7], s[4:5], v[96:97] op_sel_hi:[1,0,1]
	v_lshlrev_b32_e32 v96, 16, v98
	v_and_b32_e32 v97, 0xffff0000, v98
	v_cvt_pk_bf16_f32 v134, v8, v9
	v_pk_fma_f32 v[8:9], v[8:9], s[4:5], v[96:97] op_sel_hi:[1,0,1]
	v_lshlrev_b32_e32 v96, 16, v99
	v_and_b32_e32 v97, 0xffff0000, v99
	v_cvt_pk_bf16_f32 v135, v10, v11
	v_pk_fma_f32 v[10:11], v[10:11], s[4:5], v[96:97] op_sel_hi:[1,0,1]
	v_lshlrev_b32_e32 v96, 16, v92
	v_and_b32_e32 v97, 0xffff0000, v92
	v_lshlrev_b32_e32 v92, 16, v93
	v_and_b32_e32 v93, 0xffff0000, v93
	v_cvt_pk_bf16_f32 v137, v14, v15
	v_pk_fma_f32 v[14:15], v[14:15], s[4:5], v[92:93] op_sel_hi:[1,0,1]
	v_lshlrev_b32_e32 v92, 16, v94
	v_and_b32_e32 v93, 0xffff0000, v94
	v_cvt_pk_bf16_f32 v138, v16, v17
	v_pk_fma_f32 v[16:17], v[16:17], s[4:5], v[92:93] op_sel_hi:[1,0,1]
	v_lshlrev_b32_e32 v92, 16, v95
	v_and_b32_e32 v93, 0xffff0000, v95
	v_cvt_pk_bf16_f32 v132, v4, v5
	v_cvt_pk_bf16_f32 v136, v12, v13
	v_cvt_pk_bf16_f32 v139, v18, v19
	v_pk_fma_f32 v[4:5], v[4:5], s[4:5], v[174:175] op_sel_hi:[1,0,1]
	v_pk_fma_f32 v[12:13], v[12:13], s[4:5], v[96:97] op_sel_hi:[1,0,1]
	v_pk_fma_f32 v[18:19], v[18:19], s[4:5], v[92:93] op_sel_hi:[1,0,1]
	v_cvt_pk_bf16_f32 v141, v22, v23
	v_cvt_pk_bf16_f32 v142, v24, v25
	v_mfma_f32_32x32x16_bf16 v[4:19], v[76:79], v[132:135], v[4:19]
	v_lshlrev_b32_e32 v76, 16, v72
	v_and_b32_e32 v77, 0xffff0000, v72
	v_lshlrev_b32_e32 v72, 16, v73
	v_and_b32_e32 v73, 0xffff0000, v73
	v_fma_f32 v22, v22, s4, v72
	v_fma_f32 v23, v23, s4, v73
	v_lshlrev_b32_e32 v72, 16, v74
	v_and_b32_e32 v73, 0xffff0000, v74
	v_pk_fma_f32 v[24:25], v[24:25], s[4:5], v[72:73] op_sel_hi:[1,0,1]
	v_lshlrev_b32_e32 v72, 16, v75
	v_and_b32_e32 v73, 0xffff0000, v75
	v_cvt_pk_bf16_f32 v143, v26, v27
	v_pk_fma_f32 v[26:27], v[26:27], s[4:5], v[72:73] op_sel_hi:[1,0,1]
	v_lshlrev_b32_e32 v72, 16, v52
	v_and_b32_e32 v73, 0xffff0000, v52
	v_lshlrev_b32_e32 v52, 16, v53
	v_and_b32_e32 v53, 0xffff0000, v53
	v_cvt_pk_bf16_f32 v145, v30, v31
	v_pk_fma_f32 v[30:31], v[30:31], s[4:5], v[52:53] op_sel_hi:[1,0,1]
	v_lshlrev_b32_e32 v52, 16, v54
	v_and_b32_e32 v53, 0xffff0000, v54
	v_cvt_pk_bf16_f32 v146, v32, v33
	v_pk_fma_f32 v[32:33], v[32:33], s[4:5], v[52:53] op_sel_hi:[1,0,1]
	v_lshlrev_b32_e32 v52, 16, v55
	v_and_b32_e32 v53, 0xffff0000, v55
	v_cvt_pk_bf16_f32 v140, v20, v21
	v_cvt_pk_bf16_f32 v144, v28, v29
	v_cvt_pk_bf16_f32 v147, v34, v35
	v_pk_fma_f32 v[20:21], v[20:21], s[4:5], v[76:77] op_sel_hi:[1,0,1]
	v_pk_fma_f32 v[28:29], v[28:29], s[4:5], v[72:73] op_sel_hi:[1,0,1]
	v_pk_fma_f32 v[34:35], v[34:35], s[4:5], v[52:53] op_sel_hi:[1,0,1]
	v_mfma_f32_32x32x16_bf16 v[4:19], v[80:83], v[136:139], v[4:19]
	s_mul_i32 s4, s12, 0x3000
	v_add_u32_e32 v52, s4, v171
	s_min_i32 s4, s13, s31
	s_ashr_i32 s5, s4, 31
	s_mul_i32 s5, s0, s5
	s_mul_hi_u32 s7, s0, s4
	s_add_i32 s5, s7, s5
	v_mfma_f32_32x32x16_bf16 v[20:35], v[36:39], v[132:135], v[20:35]
	s_mul_i32 s7, s1, s4
	s_add_i32 s6, s12, 1
	s_add_i32 s5, s5, s7
	s_mul_i32 s4, s0, s4
	s_add_u32 s4, s2, s4
	s_mul_i32 s7, s11, 0x3000
	global_store_dwordx4 v[166:167], v[132:135], off offset:-2048
	global_store_dwordx4 v[166:167], v[136:139], off offset:-1024
	global_store_dwordx4 v[166:167], v[140:143], off
	global_store_dwordx4 v[166:167], v[144:147], off offset:1024
	v_mfma_f32_32x32x16_bf16 v[20:35], v[40:43], v[136:139], v[20:35]
	s_addc_u32 s5, s3, s5
	s_add_i32 s7, s22, s7
	s_waitcnt vmcnt(36)
	v_lshl_add_u64 v[132:133], s[4:5], 0, v[2:3]
	s_mov_b32 m0, s7
	v_and_b32_e32 v173, 0xffff0000, v128
	v_lshl_add_u64 v[174:175], v[166:167], 0, s[0:1]
	v_mfma_f32_32x32x16_bf16 v[4:19], v[84:87], v[140:143], v[4:19]
	v_lshl_add_u64 v[166:167], v[166:167], 0, s[8:9]
	v_mfma_f32_32x32x16_bf16 v[20:35], v[44:47], v[140:143], v[20:35]
	v_mfma_f32_32x32x16_bf16 v[4:19], v[88:91], v[144:147], v[4:19]
	v_mfma_f32_32x32x16_bf16 v[20:35], v[48:51], v[144:147], v[20:35]
	ds_read_b128 v[76:79], v52
	ds_read_b128 v[80:83], v52 offset:1024
	ds_read_b128 v[84:87], v52 offset:2048
	ds_read_b128 v[88:91], v52 offset:3072
	ds_read_b128 v[96:99], v52 offset:8192
	ds_read_b128 v[92:95], v52 offset:9216
	ds_read_b128 v[36:39], v52 offset:4096
	ds_read_b128 v[40:43], v52 offset:5120
	ds_read_b128 v[44:47], v52 offset:6144
	ds_read_b128 v[48:51], v52 offset:7168
	ds_read_b128 v[72:75], v52 offset:10240
	ds_read_b128 v[52:55], v52 offset:11264
	global_load_lds_dwordx4 v[132:133], off
	v_lshl_add_u64 v[132:133], s[4:5], 0, v[148:149]
	s_add_i32 m0, s7, 0x400
	v_cvt_pk_bf16_f32 v134, v8, v9
	global_load_lds_dwordx4 v[132:133], off
	v_lshl_add_u64 v[132:133], s[4:5], 0, v[150:151]
	s_add_i32 m0, s7, 0x800
	v_cvt_pk_bf16_f32 v135, v10, v11
	global_load_lds_dwordx4 v[132:133], off
	v_lshl_add_u64 v[132:133], s[4:5], 0, v[152:153]
	s_add_i32 m0, s7, 0xc00
	v_cvt_pk_bf16_f32 v137, v14, v15
	global_load_lds_dwordx4 v[132:133], off
	v_lshl_add_u64 v[132:133], s[4:5], 0, v[154:155]
	s_add_i32 m0, s7, 0x1000
	v_cvt_pk_bf16_f32 v138, v16, v17
	global_load_lds_dwordx4 v[132:133], off
	v_lshl_add_u64 v[132:133], s[4:5], 0, v[156:157]
	s_add_i32 m0, s7, 0x1400
; DI void phase_scan(KArgs args, LAS unsigned char* L, const Ctx& c) {
;     ...
;         SCAN_DMA(); SCAN_DMA(); SCAN_DMA(); SCAN_DMA(); SCAN_DMA();
;         asm volatile("s_waitcnt vmcnt(48)" ::: "memory"); SCAN_LOAD(0);
;         asm volatile("s_waitcnt vmcnt(36)" ::: "memory"); SCAN_LOAD(1);
;         for (int step = 0; step < nch; step += 2) {
;             SCAN_STEP(0, step);     asm volatile("s_waitcnt vmcnt(24)" ::: "memory"); SCAN_LOAD(0); SCAN_DMA();
;             SCAN_STEP(1, step + 1); asm volatile("s_waitcnt vmcnt(24)" ::: "memory"); SCAN_LOAD(1); SCAN_DMA();
;         }
;         asm volatile("s_waitcnt vmcnt(0)" ::: "memory");
	v_cvt_pk_bf16_f32 v136, v12, v13
	global_load_lds_dwordx4 v[132:133], off
	v_lshl_add_u64 v[132:133], s[4:5], 0, v[158:159]
	s_add_i32 m0, s7, 0x1800
	v_cvt_pk_bf16_f32 v139, v18, v19
	global_load_lds_dwordx4 v[132:133], off
	s_add_i32 m0, s7, 0x1c00
	v_lshl_add_u64 v[132:133], s[4:5], 0, v[160:161]
	s_add_u32 s4, s4, 0x2000
	s_addc_u32 s5, s5, 0
	global_load_lds_dwordx4 v[132:133], off
	s_add_i32 m0, s7, 0x2000
	v_lshl_add_u64 v[132:133], s[4:5], 0, v[162:163]
	global_load_lds_dwordx4 v[132:133], off
	v_lshl_add_u64 v[132:133], v[132:133], 0, 16
	s_add_i32 m0, s7, 0x2400
	v_cvt_pk_bf16_f32 v140, v20, v21
	global_load_lds_dwordx4 v[132:133], off
	v_lshl_add_u64 v[132:133], s[4:5], 0, v[164:165]
	s_add_i32 m0, s7, 0x2800
	v_cvt_pk_bf16_f32 v141, v22, v23
	global_load_lds_dwordx4 v[132:133], off
	s_add_i32 m0, s7, 0x2c00
	s_cmp_lg_u32 s12, 4
	s_cselect_b32 s6, s6, 0
	s_add_i32 s4, s11, 1
	s_cmp_lg_u32 s11, 4
	s_cselect_b32 s7, s4, 0
	s_add_i32 s4, s10, -5
	v_lshl_add_u64 v[132:133], v[132:133], 0, 16
	v_readlane_b32 s4, v172, s4
	v_lshlrev_b32_e32 v172, 16, v128
	v_lshlrev_b32_e32 v128, 16, v129
	v_and_b32_e32 v129, 0xffff0000, v129
	global_load_lds_dwordx4 v[132:133], off
	v_cvt_pk_bf16_f32 v133, v6, v7
	v_pk_fma_f32 v[6:7], v[6:7], s[4:5], v[128:129] op_sel_hi:[1,0,1]
	v_lshlrev_b32_e32 v128, 16, v130
	v_and_b32_e32 v129, 0xffff0000, v130
	v_pk_fma_f32 v[8:9], v[8:9], s[4:5], v[128:129] op_sel_hi:[1,0,1]
	v_lshlrev_b32_e32 v128, 16, v131
	v_and_b32_e32 v129, 0xffff0000, v131
	v_pk_fma_f32 v[10:11], v[10:11], s[4:5], v[128:129] op_sel_hi:[1,0,1]
	v_lshlrev_b32_e32 v128, 16, v124
	v_and_b32_e32 v129, 0xffff0000, v124
	v_lshlrev_b32_e32 v124, 16, v125
	v_and_b32_e32 v125, 0xffff0000, v125
	v_pk_fma_f32 v[14:15], v[14:15], s[4:5], v[124:125] op_sel_hi:[1,0,1]
	v_lshlrev_b32_e32 v124, 16, v126
	v_and_b32_e32 v125, 0xffff0000, v126
	v_pk_fma_f32 v[16:17], v[16:17], s[4:5], v[124:125] op_sel_hi:[1,0,1]
	v_lshlrev_b32_e32 v124, 16, v127
	v_and_b32_e32 v125, 0xffff0000, v127
	v_cvt_pk_bf16_f32 v132, v4, v5
	v_pk_fma_f32 v[4:5], v[4:5], s[4:5], v[172:173] op_sel_hi:[1,0,1]
	v_pk_fma_f32 v[12:13], v[12:13], s[4:5], v[128:129] op_sel_hi:[1,0,1]
	v_pk_fma_f32 v[18:19], v[18:19], s[4:5], v[124:125] op_sel_hi:[1,0,1]
	v_cvt_pk_bf16_f32 v142, v24, v25
	v_cvt_pk_bf16_f32 v143, v26, v27
	v_mfma_f32_32x32x16_bf16 v[4:19], v[120:123], v[132:135], v[4:19]
	v_cvt_pk_bf16_f32 v144, v28, v29
	v_cvt_pk_bf16_f32 v145, v30, v31
	v_cvt_pk_bf16_f32 v146, v32, v33
	v_cvt_pk_bf16_f32 v147, v34, v35
	s_add_i32 s11, s6, 1
	global_store_dwordx4 v[174:175], v[132:135], off offset:-2048
	global_store_dwordx4 v[174:175], v[136:139], off offset:-1024
	global_store_dwordx4 v[174:175], v[140:143], off
	global_store_dwordx4 v[174:175], v[144:147], off offset:1024
	s_waitcnt vmcnt(36)
	v_mfma_f32_32x32x16_bf16 v[4:19], v[116:119], v[136:139], v[4:19]
	v_mfma_f32_32x32x16_bf16 v[4:19], v[112:115], v[140:143], v[4:19]
	v_mfma_f32_32x32x16_bf16 v[4:19], v[108:111], v[144:147], v[4:19]
	v_lshlrev_b32_e32 v108, 16, v104
	v_and_b32_e32 v109, 0xffff0000, v104
	v_lshlrev_b32_e32 v104, 16, v105
	v_and_b32_e32 v105, 0xffff0000, v105
	v_fma_f32 v22, v22, s4, v104
	v_fma_f32 v23, v23, s4, v105
	v_lshlrev_b32_e32 v104, 16, v106
	v_and_b32_e32 v105, 0xffff0000, v106
	v_pk_fma_f32 v[24:25], v[24:25], s[4:5], v[104:105] op_sel_hi:[1,0,1]
	v_lshlrev_b32_e32 v104, 16, v107
	v_and_b32_e32 v105, 0xffff0000, v107
	v_pk_fma_f32 v[26:27], v[26:27], s[4:5], v[104:105] op_sel_hi:[1,0,1]
	v_lshlrev_b32_e32 v104, 16, v100
	v_and_b32_e32 v105, 0xffff0000, v100
	v_lshlrev_b32_e32 v100, 16, v101
	v_and_b32_e32 v101, 0xffff0000, v101
	v_pk_fma_f32 v[30:31], v[30:31], s[4:5], v[100:101] op_sel_hi:[1,0,1]
	v_lshlrev_b32_e32 v100, 16, v102
	v_and_b32_e32 v101, 0xffff0000, v102
	v_pk_fma_f32 v[32:33], v[32:33], s[4:5], v[100:101] op_sel_hi:[1,0,1]
	v_lshlrev_b32_e32 v100, 16, v103
	v_and_b32_e32 v101, 0xffff0000, v103
	v_pk_fma_f32 v[20:21], v[20:21], s[4:5], v[108:109] op_sel_hi:[1,0,1]
	v_pk_fma_f32 v[28:29], v[28:29], s[4:5], v[104:105] op_sel_hi:[1,0,1]
	v_pk_fma_f32 v[34:35], v[34:35], s[4:5], v[100:101] op_sel_hi:[1,0,1]
	s_mul_i32 s4, s6, 0x3000
	v_add_u32_e32 v100, s4, v171
	v_mfma_f32_32x32x16_bf16 v[20:35], v[68:71], v[132:135], v[20:35]
	s_min_i32 s4, s10, s31
	s_ashr_i32 s5, s4, 31
	s_mul_i32 s5, s0, s5
	s_mul_hi_u32 s12, s0, s4
	s_add_i32 s5, s12, s5
	s_mul_i32 s12, s1, s4
	s_add_i32 s5, s5, s12
	v_mfma_f32_32x32x16_bf16 v[20:35], v[64:67], v[136:139], v[20:35]
	s_mul_i32 s4, s0, s4
	s_add_u32 s4, s2, s4
	s_mul_i32 s12, s7, 0x3000
	s_addc_u32 s5, s3, s5
	s_add_i32 s12, s22, s12
	v_lshl_add_u64 v[132:133], s[4:5], 0, v[2:3]
	s_mov_b32 m0, s12
	v_mfma_f32_32x32x16_bf16 v[20:35], v[60:63], v[140:143], v[20:35]
	v_mfma_f32_32x32x16_bf16 v[20:35], v[56:59], v[144:147], v[20:35]
	ds_read_b128 v[120:123], v100
	ds_read_b128 v[116:119], v100 offset:1024
	ds_read_b128 v[112:115], v100 offset:2048
	ds_read_b128 v[108:111], v100 offset:3072
	ds_read_b128 v[128:131], v100 offset:8192
	ds_read_b128 v[124:127], v100 offset:9216
	ds_read_b128 v[68:71], v100 offset:4096
	ds_read_b128 v[64:67], v100 offset:5120
	ds_read_b128 v[60:63], v100 offset:6144
	ds_read_b128 v[56:59], v100 offset:7168
	ds_read_b128 v[104:107], v100 offset:10240
	ds_read_b128 v[100:103], v100 offset:11264
	global_load_lds_dwordx4 v[132:133], off
	v_lshl_add_u64 v[132:133], s[4:5], 0, v[148:149]
	s_add_i32 m0, s12, 0x400
	s_nop 0
	global_load_lds_dwordx4 v[132:133], off
	v_lshl_add_u64 v[132:133], s[4:5], 0, v[150:151]
	s_add_i32 m0, s12, 0x800
	s_nop 0
	global_load_lds_dwordx4 v[132:133], off
	v_lshl_add_u64 v[132:133], s[4:5], 0, v[152:153]
	s_add_i32 m0, s12, 0xc00
	s_nop 0
	global_load_lds_dwordx4 v[132:133], off
	v_lshl_add_u64 v[132:133], s[4:5], 0, v[154:155]
	s_add_i32 m0, s12, 0x1000
	s_nop 0
	global_load_lds_dwordx4 v[132:133], off
	v_lshl_add_u64 v[132:133], s[4:5], 0, v[156:157]
	s_add_i32 m0, s12, 0x1400
	s_nop 0
	global_load_lds_dwordx4 v[132:133], off
	v_lshl_add_u64 v[132:133], s[4:5], 0, v[158:159]
	s_add_i32 m0, s12, 0x1800
	s_nop 0
	global_load_lds_dwordx4 v[132:133], off
	s_add_i32 m0, s12, 0x1c00
	v_lshl_add_u64 v[132:133], s[4:5], 0, v[160:161]
	s_add_u32 s4, s4, 0x2000
	s_addc_u32 s5, s5, 0
	global_load_lds_dwordx4 v[132:133], off
	s_add_i32 m0, s12, 0x2000
	v_lshl_add_u64 v[132:133], s[4:5], 0, v[162:163]
	global_load_lds_dwordx4 v[132:133], off
	v_lshl_add_u64 v[132:133], v[132:133], 0, 16
	s_add_i32 m0, s12, 0x2400
	s_nop 0
	global_load_lds_dwordx4 v[132:133], off
	v_lshl_add_u64 v[132:133], s[4:5], 0, v[164:165]
	s_add_i32 m0, s12, 0x2800
	s_nop 0
	global_load_lds_dwordx4 v[132:133], off
	v_lshl_add_u64 v[132:133], v[132:133], 0, 16
	s_add_i32 m0, s12, 0x2c00
	s_cmp_lg_u32 s6, 4
	global_load_lds_dwordx4 v[132:133], off
	s_cselect_b32 s12, s11, 0
	s_add_i32 s4, s7, 1
	s_cmp_lg_u32 s7, 4
	s_cselect_b32 s11, s4, 0
	s_add_i32 s4, s10, 2
	s_add_i32 s5, s10, -4
	s_cmp_ge_u32 s5, s30
	s_mov_b32 s10, s4
	s_cbranch_scc0 .LBB0_649
	s_waitcnt vmcnt(0)
